# stacked: counted LDS waits in GEMM MFMA clusters on top of dead issue-slot removal
# baseline (speedup 1.0000x reference)
; #define PG8_STAGE(bufoff, gbase, voff) do { _Pragma("unroll") for (int _i = 0; _i < 2; ++_i) \
;         __builtin_amdgcn_global_load_lds((const unsigned*)((const char*)(gbase) + (voff)[_i]), (LAS unsigned*)(lds + (bufoff) + ldsw + _i * 8192), 16, 0, 0); } while (0)
; #define PG8_LDA(dst, b, h) do { _Pragma("unroll") for (int m = 0; m < 4; ++m) _Pragma("unroll") for (int k = 0; k < 2; ++k) dst[m][k] = *(const LAS bf16x8*)(lds + PG8_SA(b, h) + aoff + m * 2048 + k * 1024); } while (0)
; #define PG8_LDB(dst, b, h) do { _Pragma("unroll") for (int n = 0; n < 2; ++n) _Pragma("unroll") for (int k = 0; k < 2; ++k) dst[n][k] = *(const LAS bf16x8*)(lds + PG8_SB(b, h) + boff + n * 2048 + k * 1024); } while (0)
; #define PG8_MMA(ai, bj, At, Bt) do { __builtin_amdgcn_s_setprio(1); _Pragma("unroll") for (int m = 0; m < 4; ++m) _Pragma("unroll") for (int n = 0; n < 2; ++n) _Pragma("unroll") for (int k = 0; k < 2; ++k) \
;         acc[ai][bj][m][n] = __builtin_amdgcn_mfma_f32_16x16x32_bf16(Bt[n][k], At[m][k], acc[ai][bj][m][n], 0, 0, 0); __builtin_amdgcn_s_setprio(0); } while (0)
; #define PG8_WAIT_V(n) asm volatile("s_waitcnt vmcnt(" #n ")" ::: "memory")
; #define PG8_WAIT_L(n) asm volatile("s_waitcnt lgkmcnt(" #n ")" ::: "memory")
; #define PG8_BAR __builtin_amdgcn_s_barrier()
; #define PG8_SCHED __builtin_amdgcn_sched_barrier(0)
; __device__ __forceinline__ void gemm_phase(LAS unsigned char* lds, const Desc& g, int G, int cidx, int tid) {
;     ...
;             const bool last = (t == nt - 2);
;             const char* a1 = cA + (size_t)(t + 1) * kstep;
;             const char* a2 = last ? nA : cA + (size_t)(t + 2) * kstep; const char* b2 = last ? nB : cB + (size_t)(t + 2) * kstep;
;             const char* a3 = a2 + kstep; const char* b3 = b2 + kstep;
;             PG8_LDB(B0, 0, 0); PG8_LDB(B1, 0, 1); PG8_SCHED; PG8_LDA(At, 0, 0); PG8_STAGE(PG8_SA(1, 1), a1 + hstepA, voffA);
;             PG8_WAIT_V(8); PG8_WAIT_L(0); PG8_BAR; PG8_MMA(0, 0, At, B0); PG8_MMA(0, 1, At, B1); PG8_BAR; PG8_SCHED;
;             PG8_LDA(At, 0, 1); PG8_STAGE(PG8_SB(0, 0), b2, voffB); PG8_STAGE(PG8_SB(0, 1), b2 + hstepB, voffB); PG8_STAGE(PG8_SA(0, 0), a2, voffA);
;             PG8_WAIT_V(8); PG8_WAIT_L(0); PG8_BAR; PG8_MMA(1, 0, At, B0); PG8_MMA(1, 1, At, B1); PG8_BAR; PG8_SCHED;
.LBB0_199:
	s_add_u32 s52, s50, 0x100
	s_addc_u32 s53, s51, 0
	s_add_i32 s42, 0, 0x10000
	s_cmp_eq_u32 s63, 62
	s_cselect_b32 s59, s1, s53
	s_cselect_b32 s58, s0, s52
	v_add_u32_e32 v142, s42, v139
	s_cselect_b32 s57, s49, s62
	s_cselect_b32 s56, s48, s61
	s_add_i32 s43, 0, 0x14000
	ds_read_b128 v[156:159], v142
	ds_read_b128 v[160:163], v142 offset:1024
	ds_read_b128 v[164:167], v142 offset:2048
	ds_read_b128 v[168:171], v142 offset:3072
	v_add_u32_e32 v142, s43, v139
	ds_read_b128 v[172:175], v142
	ds_read_b128 v[176:179], v142 offset:1024
	ds_read_b128 v[180:183], v142 offset:2048
	ds_read_b128 v[184:187], v142 offset:3072
	v_lshl_add_u64 v[142:143], s[50:51], 0, v[136:137]
	s_add_i32 m0, s7, 0xc000
	ds_read_b128 v[188:191], v141
	ds_read_b128 v[192:195], v141 offset:1024
	ds_read_b128 v[196:199], v141 offset:2048
	ds_read_b128 v[206:209], v141 offset:3072
	ds_read_b128 v[210:213], v141 offset:4096
	ds_read_b128 v[214:217], v141 offset:5120
	ds_read_b128 v[218:221], v141 offset:6144
	ds_read_b128 v[222:225], v141 offset:7168
	global_load_lds_dwordx4 v[142:143], off
	v_lshl_add_u64 v[142:143], s[50:51], 0, v[134:135]
	s_add_i32 m0, s7, 0xe000
	s_nop 0
	global_load_lds_dwordx4 v[142:143], off
	s_waitcnt vmcnt(8)
	s_barrier
	s_setprio 1
	s_waitcnt lgkmcnt(7)
	v_mfma_f32_16x16x32_bf16 v[124:127], v[156:159], v[188:191], v[124:127]
	v_mfma_f32_16x16x32_bf16 v[120:123], v[164:167], v[188:191], v[120:123]
	s_waitcnt lgkmcnt(5)
	v_mfma_f32_16x16x32_bf16 v[108:111], v[156:159], v[196:199], v[108:111]
	v_mfma_f32_16x16x32_bf16 v[104:107], v[164:167], v[196:199], v[104:107]
	s_waitcnt lgkmcnt(3)
	v_mfma_f32_16x16x32_bf16 v[92:95], v[156:159], v[210:213], v[92:95]
	v_mfma_f32_16x16x32_bf16 v[88:91], v[164:167], v[210:213], v[88:91]
	s_waitcnt lgkmcnt(1)
	v_mfma_f32_16x16x32_bf16 v[76:79], v[156:159], v[218:221], v[76:79]
	v_mfma_f32_16x16x32_bf16 v[72:75], v[164:167], v[218:221], v[72:75]
	v_mfma_f32_16x16x32_bf16 v[124:127], v[160:163], v[192:195], v[124:127]
	v_mfma_f32_16x16x32_bf16 v[120:123], v[168:171], v[192:195], v[120:123]
	v_mfma_f32_16x16x32_bf16 v[108:111], v[160:163], v[206:209], v[108:111]
	v_mfma_f32_16x16x32_bf16 v[104:107], v[168:171], v[206:209], v[104:107]
	v_mfma_f32_16x16x32_bf16 v[92:95], v[160:163], v[214:217], v[92:95]
	v_mfma_f32_16x16x32_bf16 v[88:91], v[168:171], v[214:217], v[88:91]
	s_waitcnt lgkmcnt(0)
	v_mfma_f32_16x16x32_bf16 v[76:79], v[160:163], v[222:225], v[76:79]
	v_mfma_f32_16x16x32_bf16 v[72:75], v[168:171], v[222:225], v[72:75]
	v_mfma_f32_16x16x32_bf16 v[116:119], v[172:175], v[188:191], v[116:119]
	v_mfma_f32_16x16x32_bf16 v[112:115], v[180:183], v[188:191], v[112:115]
	v_mfma_f32_16x16x32_bf16 v[100:103], v[172:175], v[196:199], v[100:103]
	v_mfma_f32_16x16x32_bf16 v[96:99], v[180:183], v[196:199], v[96:99]
	v_mfma_f32_16x16x32_bf16 v[84:87], v[172:175], v[210:213], v[84:87]
	v_mfma_f32_16x16x32_bf16 v[80:83], v[180:183], v[210:213], v[80:83]
	v_mfma_f32_16x16x32_bf16 v[68:71], v[172:175], v[218:221], v[68:71]
	v_mfma_f32_16x16x32_bf16 v[64:67], v[180:183], v[218:221], v[64:67]
	v_mfma_f32_16x16x32_bf16 v[116:119], v[176:179], v[192:195], v[116:119]
	v_mfma_f32_16x16x32_bf16 v[112:115], v[184:187], v[192:195], v[112:115]
	v_mfma_f32_16x16x32_bf16 v[100:103], v[176:179], v[206:209], v[100:103]
	v_mfma_f32_16x16x32_bf16 v[96:99], v[184:187], v[206:209], v[96:99]
	v_mfma_f32_16x16x32_bf16 v[84:87], v[176:179], v[214:217], v[84:87]
	v_mfma_f32_16x16x32_bf16 v[80:83], v[184:187], v[214:217], v[80:83]
	v_mfma_f32_16x16x32_bf16 v[68:71], v[176:179], v[222:225], v[68:71]
	v_mfma_f32_16x16x32_bf16 v[64:67], v[184:187], v[222:225], v[64:67]
	s_setprio 0
	s_barrier
	s_add_i32 s42, s42, s6
	v_lshl_add_u64 v[142:143], s[56:57], 0, v[144:145]
	s_mov_b32 m0, s42
	ds_read_b128 v[188:191], v141 offset:16384
	ds_read_b128 v[192:195], v141 offset:17408
	ds_read_b128 v[196:199], v141 offset:18432
	ds_read_b128 v[206:209], v141 offset:19456
	ds_read_b128 v[210:213], v141 offset:20480
	ds_read_b128 v[214:217], v141 offset:21504
	ds_read_b128 v[218:221], v141 offset:22528
	ds_read_b128 v[222:225], v141 offset:23552
	global_load_lds_dwordx4 v[142:143], off
	s_add_i32 m0, s42, 0x2000
	s_add_u32 s50, s56, 0x110000
	v_lshl_add_u64 v[146:147], s[56:57], 0, v[128:129]
	s_addc_u32 s51, s57, 0
	s_add_i32 s42, s43, s6
	global_load_lds_dwordx4 v[146:147], off
	v_lshl_add_u64 v[148:149], s[50:51], 0, v[144:145]
	s_mov_b32 m0, s42
	v_lshl_add_u64 v[200:201], s[58:59], 0, v[130:131]
	global_load_lds_dwordx4 v[148:149], off
	v_lshl_add_u64 v[148:149], s[50:51], 0, v[128:129]
	s_add_i32 m0, s42, 0x2000
	s_nop 0
	global_load_lds_dwordx4 v[148:149], off
	v_lshl_add_u64 v[148:149], s[58:59], 0, v[132:133]
	s_mov_b32 m0, s7
	s_nop 0
	global_load_lds_dwordx4 v[148:149], off
	s_mov_b32 m0, s13
	s_nop 0
	global_load_lds_dwordx4 v[200:201], off
	s_waitcnt vmcnt(8)
	s_barrier
; #define PG8_STAGE(bufoff, gbase, voff) do { _Pragma("unroll") for (int _i = 0; _i < 2; ++_i) \
;         __builtin_amdgcn_global_load_lds((const unsigned*)((const char*)(gbase) + (voff)[_i]), (LAS unsigned*)(lds + (bufoff) + ldsw + _i * 8192), 16, 0, 0); } while (0)
; #define PG8_LDA(dst, b, h) do { _Pragma("unroll") for (int m = 0; m < 4; ++m) _Pragma("unroll") for (int k = 0; k < 2; ++k) dst[m][k] = *(const LAS bf16x8*)(lds + PG8_SA(b, h) + aoff + m * 2048 + k * 1024); } while (0)
; #define PG8_LDB(dst, b, h) do { _Pragma("unroll") for (int n = 0; n < 2; ++n) _Pragma("unroll") for (int k = 0; k < 2; ++k) dst[n][k] = *(const LAS bf16x8*)(lds + PG8_SB(b, h) + boff + n * 2048 + k * 1024); } while (0)
; #define PG8_MMA(ai, bj, At, Bt) do { __builtin_amdgcn_s_setprio(1); _Pragma("unroll") for (int m = 0; m < 4; ++m) _Pragma("unroll") for (int n = 0; n < 2; ++n) _Pragma("unroll") for (int k = 0; k < 2; ++k) \
;         acc[ai][bj][m][n] = __builtin_amdgcn_mfma_f32_16x16x32_bf16(Bt[n][k], At[m][k], acc[ai][bj][m][n], 0, 0, 0); __builtin_amdgcn_s_setprio(0); } while (0)
; #define PG8_WAIT_V(n) asm volatile("s_waitcnt vmcnt(" #n ")" ::: "memory")
; #define PG8_WAIT_L(n) asm volatile("s_waitcnt lgkmcnt(" #n ")" ::: "memory")
; #define PG8_BAR __builtin_amdgcn_s_barrier()
; #define PG8_SCHED __builtin_amdgcn_sched_barrier(0)
; __device__ __forceinline__ void gemm_phase(LAS unsigned char* lds, const Desc& g, int G, int cidx, int tid) {
;     ...
;             PG8_WAIT_V(8); PG8_WAIT_L(0); PG8_BAR; PG8_MMA(1, 0, At, B0); PG8_MMA(1, 1, At, B1); PG8_BAR; PG8_SCHED;
;             PG8_LDB(B0, 1, 0); PG8_LDB(B1, 1, 1); PG8_SCHED; PG8_LDA(At, 1, 0); PG8_STAGE(PG8_SA(0, 1), a2 + hstepA, voffA);
;             PG8_WAIT_V(8); PG8_WAIT_L(0); PG8_BAR; PG8_MMA(0, 0, At, B0); PG8_MMA(0, 1, At, B1); PG8_BAR; PG8_SCHED;
;             PG8_LDA(At, 1, 1); PG8_STAGE(PG8_SB(1, 0), b3, voffB); PG8_STAGE(PG8_SB(1, 1), b3 + hstepB, voffB); PG8_STAGE(PG8_SA(1, 0), a3, voffA);
	s_setprio 1
	s_waitcnt lgkmcnt(7)
	v_mfma_f32_16x16x32_bf16 v[60:63], v[156:159], v[188:191], v[60:63]
	v_mfma_f32_16x16x32_bf16 v[56:59], v[164:167], v[188:191], v[56:59]
	s_waitcnt lgkmcnt(5)
	v_mfma_f32_16x16x32_bf16 v[44:47], v[156:159], v[196:199], v[44:47]
	v_mfma_f32_16x16x32_bf16 v[40:43], v[164:167], v[196:199], v[40:43]
	s_waitcnt lgkmcnt(3)
	v_mfma_f32_16x16x32_bf16 v[28:31], v[156:159], v[210:213], v[28:31]
	v_mfma_f32_16x16x32_bf16 v[24:27], v[164:167], v[210:213], v[24:27]
	s_waitcnt lgkmcnt(1)
	v_mfma_f32_16x16x32_bf16 v[12:15], v[156:159], v[218:221], v[12:15]
	v_mfma_f32_16x16x32_bf16 v[8:11], v[164:167], v[218:221], v[8:11]
	v_mfma_f32_16x16x32_bf16 v[60:63], v[160:163], v[192:195], v[60:63]
	v_mfma_f32_16x16x32_bf16 v[56:59], v[168:171], v[192:195], v[56:59]
	v_mfma_f32_16x16x32_bf16 v[44:47], v[160:163], v[206:209], v[44:47]
	v_mfma_f32_16x16x32_bf16 v[40:43], v[168:171], v[206:209], v[40:43]
	v_mfma_f32_16x16x32_bf16 v[28:31], v[160:163], v[214:217], v[28:31]
	v_mfma_f32_16x16x32_bf16 v[24:27], v[168:171], v[214:217], v[24:27]
	s_waitcnt lgkmcnt(0)
	v_mfma_f32_16x16x32_bf16 v[12:15], v[160:163], v[222:225], v[12:15]
	v_mfma_f32_16x16x32_bf16 v[8:11], v[168:171], v[222:225], v[8:11]
	v_mfma_f32_16x16x32_bf16 v[52:55], v[172:175], v[188:191], v[52:55]
	v_mfma_f32_16x16x32_bf16 v[48:51], v[180:183], v[188:191], v[48:51]
	v_mfma_f32_16x16x32_bf16 v[36:39], v[172:175], v[196:199], v[36:39]
	v_mfma_f32_16x16x32_bf16 v[32:35], v[180:183], v[196:199], v[32:35]
	v_mfma_f32_16x16x32_bf16 v[20:23], v[172:175], v[210:213], v[20:23]
	v_mfma_f32_16x16x32_bf16 v[16:19], v[180:183], v[210:213], v[16:19]
	v_mfma_f32_16x16x32_bf16 v[0:3], v[172:175], v[218:221], v[0:3]
	v_mfma_f32_16x16x32_bf16 v[4:7], v[180:183], v[218:221], v[4:7]
	v_mfma_f32_16x16x32_bf16 v[52:55], v[176:179], v[192:195], v[52:55]
	v_mfma_f32_16x16x32_bf16 v[48:51], v[184:187], v[192:195], v[48:51]
	v_mfma_f32_16x16x32_bf16 v[36:39], v[176:179], v[206:209], v[36:39]
	v_mfma_f32_16x16x32_bf16 v[32:35], v[184:187], v[206:209], v[32:35]
	v_mfma_f32_16x16x32_bf16 v[20:23], v[176:179], v[214:217], v[20:23]
	v_mfma_f32_16x16x32_bf16 v[16:19], v[184:187], v[214:217], v[16:19]
	v_mfma_f32_16x16x32_bf16 v[0:3], v[176:179], v[222:225], v[0:3]
	v_mfma_f32_16x16x32_bf16 v[4:7], v[184:187], v[222:225], v[4:7]
	s_setprio 0
	s_barrier
	s_add_i32 s42, 0, 0x18000
	v_add_u32_e32 v155, s42, v139
	s_add_i32 s43, 0, 0x1c000
	ds_read_b128 v[156:159], v155
	ds_read_b128 v[160:163], v155 offset:1024
	ds_read_b128 v[164:167], v155 offset:2048
	ds_read_b128 v[168:171], v155 offset:3072
	v_add_u32_e32 v155, s43, v139
	ds_read_b128 v[172:175], v155
	ds_read_b128 v[176:179], v155 offset:1024
	ds_read_b128 v[180:183], v155 offset:2048
	ds_read_b128 v[184:187], v155 offset:3072
	s_add_u32 s50, s58, 0x110000
	s_addc_u32 s51, s59, 0
	s_mov_b32 m0, s18
	v_lshl_add_u64 v[226:227], s[50:51], 0, v[132:133]
	ds_read_b128 v[188:191], v141 offset:32768
	ds_read_b128 v[192:195], v141 offset:33792
	ds_read_b128 v[196:199], v141 offset:34816
	ds_read_b128 v[206:209], v141 offset:35840
	ds_read_b128 v[210:213], v141 offset:36864
	ds_read_b128 v[214:217], v141 offset:37888
	ds_read_b128 v[218:221], v141 offset:38912
	ds_read_b128 v[222:225], v141 offset:39936
	global_load_lds_dwordx4 v[226:227], off
	v_lshl_add_u64 v[226:227], s[50:51], 0, v[130:131]
	s_mov_b32 m0, s24
	s_nop 0
	global_load_lds_dwordx4 v[226:227], off
	s_waitcnt vmcnt(8)
	s_barrier
	s_setprio 1
	s_waitcnt lgkmcnt(7)
	v_mfma_f32_16x16x32_bf16 v[124:127], v[156:159], v[188:191], v[124:127]
	v_mfma_f32_16x16x32_bf16 v[120:123], v[164:167], v[188:191], v[120:123]
	s_waitcnt lgkmcnt(5)
	v_mfma_f32_16x16x32_bf16 v[108:111], v[156:159], v[196:199], v[108:111]
	v_mfma_f32_16x16x32_bf16 v[104:107], v[164:167], v[196:199], v[104:107]
	s_waitcnt lgkmcnt(3)
	v_mfma_f32_16x16x32_bf16 v[92:95], v[156:159], v[210:213], v[92:95]
	v_mfma_f32_16x16x32_bf16 v[88:91], v[164:167], v[210:213], v[88:91]
	s_waitcnt lgkmcnt(1)
	v_mfma_f32_16x16x32_bf16 v[76:79], v[156:159], v[218:221], v[76:79]
	v_mfma_f32_16x16x32_bf16 v[72:75], v[164:167], v[218:221], v[72:75]
	v_mfma_f32_16x16x32_bf16 v[124:127], v[160:163], v[192:195], v[124:127]
	v_mfma_f32_16x16x32_bf16 v[120:123], v[168:171], v[192:195], v[120:123]
	v_mfma_f32_16x16x32_bf16 v[108:111], v[160:163], v[206:209], v[108:111]
	v_mfma_f32_16x16x32_bf16 v[104:107], v[168:171], v[206:209], v[104:107]
	v_mfma_f32_16x16x32_bf16 v[92:95], v[160:163], v[214:217], v[92:95]
	v_mfma_f32_16x16x32_bf16 v[88:91], v[168:171], v[214:217], v[88:91]
	s_waitcnt lgkmcnt(0)
	v_mfma_f32_16x16x32_bf16 v[76:79], v[160:163], v[222:225], v[76:79]
	v_mfma_f32_16x16x32_bf16 v[72:75], v[168:171], v[222:225], v[72:75]
	v_mfma_f32_16x16x32_bf16 v[116:119], v[172:175], v[188:191], v[116:119]
	v_mfma_f32_16x16x32_bf16 v[112:115], v[180:183], v[188:191], v[112:115]
	v_mfma_f32_16x16x32_bf16 v[100:103], v[172:175], v[196:199], v[100:103]
	v_mfma_f32_16x16x32_bf16 v[96:99], v[180:183], v[196:199], v[96:99]
	v_mfma_f32_16x16x32_bf16 v[84:87], v[172:175], v[210:213], v[84:87]
	v_mfma_f32_16x16x32_bf16 v[80:83], v[180:183], v[210:213], v[80:83]
	v_mfma_f32_16x16x32_bf16 v[68:71], v[172:175], v[218:221], v[68:71]
	v_mfma_f32_16x16x32_bf16 v[64:67], v[180:183], v[218:221], v[64:67]
	v_mfma_f32_16x16x32_bf16 v[116:119], v[176:179], v[192:195], v[116:119]
	v_mfma_f32_16x16x32_bf16 v[112:115], v[184:187], v[192:195], v[112:115]
	v_mfma_f32_16x16x32_bf16 v[100:103], v[176:179], v[206:209], v[100:103]
	v_mfma_f32_16x16x32_bf16 v[96:99], v[184:187], v[206:209], v[96:99]
	v_mfma_f32_16x16x32_bf16 v[84:87], v[176:179], v[214:217], v[84:87]
	v_mfma_f32_16x16x32_bf16 v[80:83], v[184:187], v[214:217], v[80:83]
	v_mfma_f32_16x16x32_bf16 v[68:71], v[176:179], v[222:225], v[68:71]
	v_mfma_f32_16x16x32_bf16 v[64:67], v[184:187], v[222:225], v[64:67]
	s_setprio 0
	s_barrier
; #define PG8_STAGE(bufoff, gbase, voff) do { _Pragma("unroll") for (int _i = 0; _i < 2; ++_i) \
;         __builtin_amdgcn_global_load_lds((const unsigned*)((const char*)(gbase) + (voff)[_i]), (LAS unsigned*)(lds + (bufoff) + ldsw + _i * 8192), 16, 0, 0); } while (0)
; #define PG8_LDA(dst, b, h) do { _Pragma("unroll") for (int m = 0; m < 4; ++m) _Pragma("unroll") for (int k = 0; k < 2; ++k) dst[m][k] = *(const LAS bf16x8*)(lds + PG8_SA(b, h) + aoff + m * 2048 + k * 1024); } while (0)
; #define PG8_MMA(ai, bj, At, Bt) do { __builtin_amdgcn_s_setprio(1); _Pragma("unroll") for (int m = 0; m < 4; ++m) _Pragma("unroll") for (int n = 0; n < 2; ++n) _Pragma("unroll") for (int k = 0; k < 2; ++k) \
;         acc[ai][bj][m][n] = __builtin_amdgcn_mfma_f32_16x16x32_bf16(Bt[n][k], At[m][k], acc[ai][bj][m][n], 0, 0, 0); __builtin_amdgcn_s_setprio(0); } while (0)
; #define PG8_WAIT_V(n) asm volatile("s_waitcnt vmcnt(" #n ")" ::: "memory")
; #define PG8_WAIT_L(n) asm volatile("s_waitcnt lgkmcnt(" #n ")" ::: "memory")
; #define PG8_BAR __builtin_amdgcn_s_barrier()
; #define PG8_SCHED __builtin_amdgcn_sched_barrier(0)
; __device__ __forceinline__ void gemm_phase(LAS unsigned char* lds, const Desc& g, int G, int cidx, int tid) {
;     ...
;             PG8_LDA(At, 1, 1); PG8_STAGE(PG8_SB(1, 0), b3, voffB); PG8_STAGE(PG8_SB(1, 1), b3 + hstepB, voffB); PG8_STAGE(PG8_SA(1, 0), a3, voffA);
;             PG8_WAIT_V(8); PG8_WAIT_L(0); PG8_BAR; PG8_MMA(1, 0, At, B0); PG8_MMA(1, 1, At, B1); PG8_BAR; PG8_SCHED;
;         }
;         if (wr == 0) PG8_BAR;
	s_add_i32 s42, s42, s6
	v_lshl_add_u64 v[142:143], v[142:143], 0, s[22:23]
	s_mov_b32 m0, s42
	ds_read_b128 v[188:191], v141 offset:49152
	ds_read_b128 v[192:195], v141 offset:50176
	ds_read_b128 v[196:199], v141 offset:51200
	ds_read_b128 v[206:209], v141 offset:52224
	ds_read_b128 v[210:213], v141 offset:53248
	ds_read_b128 v[214:217], v141 offset:54272
	ds_read_b128 v[218:221], v141 offset:55296
	ds_read_b128 v[222:225], v141 offset:56320
	global_load_lds_dwordx4 v[142:143], off
	s_add_i32 m0, s42, 0x2000
	s_add_u32 s50, s56, 0x110080
	v_lshl_add_u64 v[142:143], v[146:147], 0, s[22:23]
	s_addc_u32 s51, s57, 0
	s_add_i32 s42, s43, s6
	global_load_lds_dwordx4 v[142:143], off
	v_lshl_add_u64 v[142:143], s[50:51], 0, v[144:145]
	s_mov_b32 m0, s42
	s_nop 0
	global_load_lds_dwordx4 v[142:143], off
	v_lshl_add_u64 v[142:143], s[50:51], 0, v[128:129]
	s_add_i32 m0, s42, 0x2000
	s_nop 0
	global_load_lds_dwordx4 v[142:143], off
	v_lshl_add_u64 v[142:143], v[148:149], 0, s[22:23]
	s_mov_b32 m0, s26
	s_nop 0
	global_load_lds_dwordx4 v[142:143], off
	v_lshl_add_u64 v[142:143], v[200:201], 0, s[22:23]
	s_mov_b32 m0, s28
	s_nop 0
	global_load_lds_dwordx4 v[142:143], off
	s_waitcnt vmcnt(8)
	s_barrier
	s_setprio 1
	s_waitcnt lgkmcnt(7)
	v_mfma_f32_16x16x32_bf16 v[60:63], v[156:159], v[188:191], v[60:63]
	v_mfma_f32_16x16x32_bf16 v[56:59], v[164:167], v[188:191], v[56:59]
	s_waitcnt lgkmcnt(5)
	v_mfma_f32_16x16x32_bf16 v[44:47], v[156:159], v[196:199], v[44:47]
	v_mfma_f32_16x16x32_bf16 v[40:43], v[164:167], v[196:199], v[40:43]
	s_waitcnt lgkmcnt(3)
	v_mfma_f32_16x16x32_bf16 v[28:31], v[156:159], v[210:213], v[28:31]
	v_mfma_f32_16x16x32_bf16 v[24:27], v[164:167], v[210:213], v[24:27]
	s_waitcnt lgkmcnt(1)
	v_mfma_f32_16x16x32_bf16 v[12:15], v[156:159], v[218:221], v[12:15]
	v_mfma_f32_16x16x32_bf16 v[8:11], v[164:167], v[218:221], v[8:11]
	v_mfma_f32_16x16x32_bf16 v[60:63], v[160:163], v[192:195], v[60:63]
	v_mfma_f32_16x16x32_bf16 v[56:59], v[168:171], v[192:195], v[56:59]
	v_mfma_f32_16x16x32_bf16 v[44:47], v[160:163], v[206:209], v[44:47]
	v_mfma_f32_16x16x32_bf16 v[40:43], v[168:171], v[206:209], v[40:43]
	v_mfma_f32_16x16x32_bf16 v[28:31], v[160:163], v[214:217], v[28:31]
	v_mfma_f32_16x16x32_bf16 v[24:27], v[168:171], v[214:217], v[24:27]
	s_waitcnt lgkmcnt(0)
	v_mfma_f32_16x16x32_bf16 v[12:15], v[160:163], v[222:225], v[12:15]
	v_mfma_f32_16x16x32_bf16 v[8:11], v[168:171], v[222:225], v[8:11]
	v_mfma_f32_16x16x32_bf16 v[52:55], v[172:175], v[188:191], v[52:55]
	v_mfma_f32_16x16x32_bf16 v[48:51], v[180:183], v[188:191], v[48:51]
	v_mfma_f32_16x16x32_bf16 v[36:39], v[172:175], v[196:199], v[36:39]
	v_mfma_f32_16x16x32_bf16 v[32:35], v[180:183], v[196:199], v[32:35]
	v_mfma_f32_16x16x32_bf16 v[20:23], v[172:175], v[210:213], v[20:23]
	v_mfma_f32_16x16x32_bf16 v[16:19], v[180:183], v[210:213], v[16:19]
	v_mfma_f32_16x16x32_bf16 v[0:3], v[172:175], v[218:221], v[0:3]
	v_mfma_f32_16x16x32_bf16 v[4:7], v[180:183], v[218:221], v[4:7]
	v_mfma_f32_16x16x32_bf16 v[52:55], v[176:179], v[192:195], v[52:55]
	v_mfma_f32_16x16x32_bf16 v[48:51], v[184:187], v[192:195], v[48:51]
	v_mfma_f32_16x16x32_bf16 v[36:39], v[176:179], v[206:209], v[36:39]
	v_mfma_f32_16x16x32_bf16 v[32:35], v[184:187], v[206:209], v[32:35]
	v_mfma_f32_16x16x32_bf16 v[20:23], v[176:179], v[214:217], v[20:23]
	v_mfma_f32_16x16x32_bf16 v[16:19], v[184:187], v[214:217], v[16:19]
	v_mfma_f32_16x16x32_bf16 v[0:3], v[176:179], v[222:225], v[0:3]
	v_mfma_f32_16x16x32_bf16 v[4:7], v[184:187], v[222:225], v[4:7]
	s_setprio 0
	s_barrier
	s_add_i32 s63, s63, 2
	s_add_u32 s61, s61, 0x100
	s_addc_u32 s62, s62, 0
	s_cmp_gt_u32 s63, 63
	s_mov_b64 s[50:51], s[52:53]
	s_cbranch_scc0 .LBB0_199
	s_and_b64 vcc, exec, s[36:37]
	s_cbranch_vccz .LBB0_202
	s_barrier

; #define PG8_STAGE(bufoff, gbase, voff) do { _Pragma("unroll") for (int _i = 0; _i < 2; ++_i) \
;         __builtin_amdgcn_global_load_lds((const unsigned*)((const char*)(gbase) + (voff)[_i]), (LAS unsigned*)(lds + (bufoff) + ldsw + _i * 8192), 16, 0, 0); } while (0)
; #define PG8_LDA(dst, b, h) do { _Pragma("unroll") for (int m = 0; m < 4; ++m) _Pragma("unroll") for (int k = 0; k < 2; ++k) dst[m][k] = *(const LAS bf16x8*)(lds + PG8_SA(b, h) + aoff + m * 2048 + k * 1024); } while (0)
; #define PG8_LDB(dst, b, h) do { _Pragma("unroll") for (int n = 0; n < 2; ++n) _Pragma("unroll") for (int k = 0; k < 2; ++k) dst[n][k] = *(const LAS bf16x8*)(lds + PG8_SB(b, h) + boff + n * 2048 + k * 1024); } while (0)
; #define PG8_MMA(ai, bj, At, Bt) do { __builtin_amdgcn_s_setprio(1); _Pragma("unroll") for (int m = 0; m < 4; ++m) _Pragma("unroll") for (int n = 0; n < 2; ++n) _Pragma("unroll") for (int k = 0; k < 2; ++k) \
;         acc[ai][bj][m][n] = __builtin_amdgcn_mfma_f32_16x16x32_bf16(Bt[n][k], At[m][k], acc[ai][bj][m][n], 0, 0, 0); __builtin_amdgcn_s_setprio(0); } while (0)
; #define PG8_WAIT_V(n) asm volatile("s_waitcnt vmcnt(" #n ")" ::: "memory")
; #define PG8_WAIT_L(n) asm volatile("s_waitcnt lgkmcnt(" #n ")" ::: "memory")
; #define PG8_BAR __builtin_amdgcn_s_barrier()
; #define PG8_SCHED __builtin_amdgcn_sched_barrier(0)
; __device__ __forceinline__ void gemm_phase(LAS unsigned char* lds, const Desc& g, int G, int cidx, int tid) {
;     ...
;             const bool last = (t == nt - 2);
;             const char* a1 = cA + (size_t)(t + 1) * kstep;
;             const char* a2 = last ? nA : cA + (size_t)(t + 2) * kstep; const char* b2 = last ? nB : cB + (size_t)(t + 2) * kstep;
;             const char* a3 = a2 + kstep; const char* b3 = b2 + kstep;
;             PG8_LDB(B0, 0, 0); PG8_LDB(B1, 0, 1); PG8_SCHED; PG8_LDA(At, 0, 0); PG8_STAGE(PG8_SA(1, 1), a1 + hstepA, voffA);
;             PG8_WAIT_V(8); PG8_WAIT_L(0); PG8_BAR; PG8_MMA(0, 0, At, B0); PG8_MMA(0, 1, At, B1); PG8_BAR; PG8_SCHED;
;             PG8_LDA(At, 0, 1); PG8_STAGE(PG8_SB(0, 0), b2, voffB); PG8_STAGE(PG8_SB(0, 1), b2 + hstepB, voffB); PG8_STAGE(PG8_SA(0, 0), a2, voffA);
;             PG8_WAIT_V(8); PG8_WAIT_L(0); PG8_BAR; PG8_MMA(1, 0, At, B0); PG8_MMA(1, 1, At, B1); PG8_BAR; PG8_SCHED;
.LBB0_310:
	s_add_i32 s72, s40, 2
	s_add_u32 s4, s0, 0x80
	s_addc_u32 s5, s1, 0
	s_add_i32 s73, 0, 0x10000
	s_cmp_eq_u32 s60, s40
	s_cselect_b32 s41, s69, s5
	s_cselect_b32 s40, s68, s4
	v_add_u32_e32 v144, s73, v170
	s_cselect_b32 s43, s71, s75
	s_cselect_b32 s42, s70, s67
	s_add_i32 s4, 0, 0x14000
	ds_read_b128 v[128:131], v144
	ds_read_b128 v[132:135], v144 offset:1024
	ds_read_b128 v[146:149], v144 offset:2048
	ds_read_b128 v[158:161], v144 offset:3072
	v_add_u32_e32 v144, s4, v170
	ds_read_b128 v[162:165], v144
	ds_read_b128 v[166:169], v144 offset:1024
	ds_read_b128 v[174:177], v144 offset:2048
	ds_read_b128 v[178:181], v144 offset:3072
	v_lshl_add_u64 v[218:219], s[0:1], 0, v[156:157]
	s_add_i32 m0, s89, 0xc000
	ds_read_b128 v[182:185], v172
	ds_read_b128 v[186:189], v172 offset:1024
	ds_read_b128 v[190:193], v172 offset:2048
	ds_read_b128 v[194:197], v172 offset:3072
	ds_read_b128 v[198:201], v172 offset:4096
	ds_read_b128 v[206:209], v172 offset:5120
	ds_read_b128 v[210:213], v172 offset:6144
	ds_read_b128 v[214:217], v172 offset:7168
	global_load_lds_dwordx4 v[218:219], off
	v_lshl_add_u64 v[218:219], s[0:1], 0, v[154:155]
	s_add_i32 m0, s89, 0xe000
	s_nop 0
	global_load_lds_dwordx4 v[218:219], off
	s_waitcnt vmcnt(8)
	s_barrier
	s_setprio 1
	s_waitcnt lgkmcnt(7)
	v_mfma_f32_16x16x32_bf16 v[124:127], v[128:131], v[182:185], v[124:127]
	v_mfma_f32_16x16x32_bf16 v[120:123], v[146:149], v[182:185], v[120:123]
	s_waitcnt lgkmcnt(5)
	v_mfma_f32_16x16x32_bf16 v[108:111], v[128:131], v[190:193], v[108:111]
	v_mfma_f32_16x16x32_bf16 v[104:107], v[146:149], v[190:193], v[104:107]
	s_waitcnt lgkmcnt(3)
	v_mfma_f32_16x16x32_bf16 v[92:95], v[128:131], v[198:201], v[92:95]
	v_mfma_f32_16x16x32_bf16 v[88:91], v[146:149], v[198:201], v[88:91]
	s_waitcnt lgkmcnt(1)
	v_mfma_f32_16x16x32_bf16 v[76:79], v[128:131], v[210:213], v[76:79]
	v_mfma_f32_16x16x32_bf16 v[72:75], v[146:149], v[210:213], v[72:75]
	v_mfma_f32_16x16x32_bf16 v[124:127], v[132:135], v[186:189], v[124:127]
	v_mfma_f32_16x16x32_bf16 v[120:123], v[158:161], v[186:189], v[120:123]
	v_mfma_f32_16x16x32_bf16 v[108:111], v[132:135], v[194:197], v[108:111]
	v_mfma_f32_16x16x32_bf16 v[104:107], v[158:161], v[194:197], v[104:107]
	v_mfma_f32_16x16x32_bf16 v[92:95], v[132:135], v[206:209], v[92:95]
	v_mfma_f32_16x16x32_bf16 v[88:91], v[158:161], v[206:209], v[88:91]
	s_waitcnt lgkmcnt(0)
	v_mfma_f32_16x16x32_bf16 v[76:79], v[132:135], v[214:217], v[76:79]
	v_mfma_f32_16x16x32_bf16 v[72:75], v[158:161], v[214:217], v[72:75]
	v_mfma_f32_16x16x32_bf16 v[116:119], v[162:165], v[182:185], v[116:119]
	v_mfma_f32_16x16x32_bf16 v[112:115], v[174:177], v[182:185], v[112:115]
	v_mfma_f32_16x16x32_bf16 v[100:103], v[162:165], v[190:193], v[100:103]
	v_mfma_f32_16x16x32_bf16 v[96:99], v[174:177], v[190:193], v[96:99]
	v_mfma_f32_16x16x32_bf16 v[84:87], v[162:165], v[198:201], v[84:87]
	v_mfma_f32_16x16x32_bf16 v[80:83], v[174:177], v[198:201], v[80:83]
	v_mfma_f32_16x16x32_bf16 v[68:71], v[162:165], v[210:213], v[68:71]
	v_mfma_f32_16x16x32_bf16 v[64:67], v[174:177], v[210:213], v[64:67]
	v_mfma_f32_16x16x32_bf16 v[116:119], v[166:169], v[186:189], v[116:119]
	v_mfma_f32_16x16x32_bf16 v[112:115], v[178:181], v[186:189], v[112:115]
	v_mfma_f32_16x16x32_bf16 v[100:103], v[166:169], v[194:197], v[100:103]
	v_mfma_f32_16x16x32_bf16 v[96:99], v[178:181], v[194:197], v[96:99]
	v_mfma_f32_16x16x32_bf16 v[84:87], v[166:169], v[206:209], v[84:87]
	v_mfma_f32_16x16x32_bf16 v[80:83], v[178:181], v[206:209], v[80:83]
	v_mfma_f32_16x16x32_bf16 v[68:71], v[166:169], v[214:217], v[68:71]
	v_mfma_f32_16x16x32_bf16 v[64:67], v[178:181], v[214:217], v[64:67]
	s_setprio 0
	s_barrier
	s_add_i32 s5, s73, s88
	v_lshl_add_u64 v[218:219], s[42:43], 0, v[138:139]
	s_mov_b32 m0, s5
	ds_read_b128 v[182:185], v172 offset:16384
	ds_read_b128 v[186:189], v172 offset:17408
	ds_read_b128 v[190:193], v172 offset:18432
	ds_read_b128 v[194:197], v172 offset:19456
	ds_read_b128 v[198:201], v172 offset:20480
	ds_read_b128 v[206:209], v172 offset:21504
	ds_read_b128 v[210:213], v172 offset:22528
	ds_read_b128 v[214:217], v172 offset:23552
	global_load_lds_dwordx4 v[218:219], off
	s_add_i32 m0, s5, 0x2000
	v_lshl_add_u64 v[220:221], s[42:43], 0, v[142:143]
	s_add_u32 s42, s42, s99
	s_addc_u32 s43, s43, 0
	s_add_i32 s4, s4, s88
	global_load_lds_dwordx4 v[220:221], off
	v_lshl_add_u64 v[222:223], s[42:43], 0, v[138:139]
	s_mov_b32 m0, s4
	v_lshl_add_u64 v[224:225], s[42:43], 0, v[142:143]
	global_load_lds_dwordx4 v[222:223], off
	s_add_i32 m0, s4, 0x2000
	v_lshl_add_u64 v[226:227], s[40:41], 0, v[136:137]
	global_load_lds_dwordx4 v[224:225], off
	s_mov_b32 m0, s89
	v_lshl_add_u64 v[228:229], s[40:41], 0, v[140:141]
	global_load_lds_dwordx4 v[226:227], off
	s_mov_b32 m0, s90
	s_nop 0
	global_load_lds_dwordx4 v[228:229], off
	s_waitcnt vmcnt(8)
	s_barrier
; #define PG8_STAGE(bufoff, gbase, voff) do { _Pragma("unroll") for (int _i = 0; _i < 2; ++_i) \
;         __builtin_amdgcn_global_load_lds((const unsigned*)((const char*)(gbase) + (voff)[_i]), (LAS unsigned*)(lds + (bufoff) + ldsw + _i * 8192), 16, 0, 0); } while (0)
; #define PG8_LDA(dst, b, h) do { _Pragma("unroll") for (int m = 0; m < 4; ++m) _Pragma("unroll") for (int k = 0; k < 2; ++k) dst[m][k] = *(const LAS bf16x8*)(lds + PG8_SA(b, h) + aoff + m * 2048 + k * 1024); } while (0)
; #define PG8_LDB(dst, b, h) do { _Pragma("unroll") for (int n = 0; n < 2; ++n) _Pragma("unroll") for (int k = 0; k < 2; ++k) dst[n][k] = *(const LAS bf16x8*)(lds + PG8_SB(b, h) + boff + n * 2048 + k * 1024); } while (0)
; #define PG8_MMA(ai, bj, At, Bt) do { __builtin_amdgcn_s_setprio(1); _Pragma("unroll") for (int m = 0; m < 4; ++m) _Pragma("unroll") for (int n = 0; n < 2; ++n) _Pragma("unroll") for (int k = 0; k < 2; ++k) \
;         acc[ai][bj][m][n] = __builtin_amdgcn_mfma_f32_16x16x32_bf16(Bt[n][k], At[m][k], acc[ai][bj][m][n], 0, 0, 0); __builtin_amdgcn_s_setprio(0); } while (0)
; #define PG8_WAIT_V(n) asm volatile("s_waitcnt vmcnt(" #n ")" ::: "memory")
; #define PG8_WAIT_L(n) asm volatile("s_waitcnt lgkmcnt(" #n ")" ::: "memory")
; #define PG8_BAR __builtin_amdgcn_s_barrier()
; #define PG8_SCHED __builtin_amdgcn_sched_barrier(0)
; __device__ __forceinline__ void gemm_phase(LAS unsigned char* lds, const Desc& g, int G, int cidx, int tid) {
;     ...
;             PG8_WAIT_V(8); PG8_WAIT_L(0); PG8_BAR; PG8_MMA(1, 0, At, B0); PG8_MMA(1, 1, At, B1); PG8_BAR; PG8_SCHED;
;             PG8_LDB(B0, 1, 0); PG8_LDB(B1, 1, 1); PG8_SCHED; PG8_LDA(At, 1, 0); PG8_STAGE(PG8_SA(0, 1), a2 + hstepA, voffA);
;             PG8_WAIT_V(8); PG8_WAIT_L(0); PG8_BAR; PG8_MMA(0, 0, At, B0); PG8_MMA(0, 1, At, B1); PG8_BAR; PG8_SCHED;
;             PG8_LDA(At, 1, 1); PG8_STAGE(PG8_SB(1, 0), b3, voffB); PG8_STAGE(PG8_SB(1, 1), b3 + hstepB, voffB); PG8_STAGE(PG8_SA(1, 0), a3, voffA);
	s_setprio 1
	s_waitcnt lgkmcnt(7)
	v_mfma_f32_16x16x32_bf16 v[60:63], v[128:131], v[182:185], v[60:63]
	v_mfma_f32_16x16x32_bf16 v[56:59], v[146:149], v[182:185], v[56:59]
	s_waitcnt lgkmcnt(5)
	v_mfma_f32_16x16x32_bf16 v[44:47], v[128:131], v[190:193], v[44:47]
	v_mfma_f32_16x16x32_bf16 v[40:43], v[146:149], v[190:193], v[40:43]
	s_waitcnt lgkmcnt(3)
	v_mfma_f32_16x16x32_bf16 v[28:31], v[128:131], v[198:201], v[28:31]
	v_mfma_f32_16x16x32_bf16 v[24:27], v[146:149], v[198:201], v[24:27]
	s_waitcnt lgkmcnt(1)
	v_mfma_f32_16x16x32_bf16 v[12:15], v[128:131], v[210:213], v[12:15]
	v_mfma_f32_16x16x32_bf16 v[8:11], v[146:149], v[210:213], v[8:11]
	v_mfma_f32_16x16x32_bf16 v[60:63], v[132:135], v[186:189], v[60:63]
	v_mfma_f32_16x16x32_bf16 v[56:59], v[158:161], v[186:189], v[56:59]
	v_mfma_f32_16x16x32_bf16 v[44:47], v[132:135], v[194:197], v[44:47]
	v_mfma_f32_16x16x32_bf16 v[40:43], v[158:161], v[194:197], v[40:43]
	v_mfma_f32_16x16x32_bf16 v[28:31], v[132:135], v[206:209], v[28:31]
	v_mfma_f32_16x16x32_bf16 v[24:27], v[158:161], v[206:209], v[24:27]
	s_waitcnt lgkmcnt(0)
	v_mfma_f32_16x16x32_bf16 v[12:15], v[132:135], v[214:217], v[12:15]
	v_mfma_f32_16x16x32_bf16 v[8:11], v[158:161], v[214:217], v[8:11]
	v_mfma_f32_16x16x32_bf16 v[52:55], v[162:165], v[182:185], v[52:55]
	v_mfma_f32_16x16x32_bf16 v[48:51], v[174:177], v[182:185], v[48:51]
	v_mfma_f32_16x16x32_bf16 v[36:39], v[162:165], v[190:193], v[36:39]
	v_mfma_f32_16x16x32_bf16 v[32:35], v[174:177], v[190:193], v[32:35]
	v_mfma_f32_16x16x32_bf16 v[20:23], v[162:165], v[198:201], v[20:23]
	v_mfma_f32_16x16x32_bf16 v[16:19], v[174:177], v[198:201], v[16:19]
	v_mfma_f32_16x16x32_bf16 v[0:3], v[162:165], v[210:213], v[0:3]
	v_mfma_f32_16x16x32_bf16 v[4:7], v[174:177], v[210:213], v[4:7]
	v_mfma_f32_16x16x32_bf16 v[52:55], v[166:169], v[186:189], v[52:55]
	v_mfma_f32_16x16x32_bf16 v[48:51], v[178:181], v[186:189], v[48:51]
	v_mfma_f32_16x16x32_bf16 v[36:39], v[166:169], v[194:197], v[36:39]
	v_mfma_f32_16x16x32_bf16 v[32:35], v[178:181], v[194:197], v[32:35]
	v_mfma_f32_16x16x32_bf16 v[20:23], v[166:169], v[206:209], v[20:23]
	v_mfma_f32_16x16x32_bf16 v[16:19], v[178:181], v[206:209], v[16:19]
	v_mfma_f32_16x16x32_bf16 v[0:3], v[166:169], v[214:217], v[0:3]
	v_mfma_f32_16x16x32_bf16 v[4:7], v[178:181], v[214:217], v[4:7]
	s_setprio 0
	s_barrier
	s_add_i32 s4, 0, 0x18000
	v_add_u32_e32 v144, s4, v170
	s_add_i32 s5, 0, 0x1c000
	ds_read_b128 v[128:131], v144
	ds_read_b128 v[132:135], v144 offset:1024
	ds_read_b128 v[146:149], v144 offset:2048
	ds_read_b128 v[158:161], v144 offset:3072
	v_add_u32_e32 v144, s5, v170
	ds_read_b128 v[162:165], v144
	ds_read_b128 v[166:169], v144 offset:1024
	ds_read_b128 v[174:177], v144 offset:2048
	ds_read_b128 v[178:181], v144 offset:3072
	s_add_u32 s40, s40, s2
	s_addc_u32 s41, s41, 0
	s_mov_b32 m0, s91
	v_lshl_add_u64 v[230:231], s[40:41], 0, v[136:137]
	ds_read_b128 v[182:185], v172 offset:32768
	ds_read_b128 v[186:189], v172 offset:33792
	ds_read_b128 v[190:193], v172 offset:34816
	ds_read_b128 v[194:197], v172 offset:35840
	ds_read_b128 v[198:201], v172 offset:36864
	ds_read_b128 v[206:209], v172 offset:37888
	ds_read_b128 v[210:213], v172 offset:38912
	ds_read_b128 v[214:217], v172 offset:39936
	global_load_lds_dwordx4 v[230:231], off
	v_lshl_add_u64 v[230:231], s[40:41], 0, v[140:141]
	s_mov_b32 m0, s92
	s_nop 0
	global_load_lds_dwordx4 v[230:231], off
	s_waitcnt vmcnt(8)
	s_barrier
	s_setprio 1
	s_waitcnt lgkmcnt(7)
	v_mfma_f32_16x16x32_bf16 v[124:127], v[128:131], v[182:185], v[124:127]
	v_mfma_f32_16x16x32_bf16 v[120:123], v[146:149], v[182:185], v[120:123]
	s_waitcnt lgkmcnt(5)
	v_mfma_f32_16x16x32_bf16 v[108:111], v[128:131], v[190:193], v[108:111]
	v_mfma_f32_16x16x32_bf16 v[104:107], v[146:149], v[190:193], v[104:107]
	s_waitcnt lgkmcnt(3)
	v_mfma_f32_16x16x32_bf16 v[92:95], v[128:131], v[198:201], v[92:95]
	v_mfma_f32_16x16x32_bf16 v[88:91], v[146:149], v[198:201], v[88:91]
	s_waitcnt lgkmcnt(1)
	v_mfma_f32_16x16x32_bf16 v[76:79], v[128:131], v[210:213], v[76:79]
	v_mfma_f32_16x16x32_bf16 v[72:75], v[146:149], v[210:213], v[72:75]
	v_mfma_f32_16x16x32_bf16 v[124:127], v[132:135], v[186:189], v[124:127]
	v_mfma_f32_16x16x32_bf16 v[120:123], v[158:161], v[186:189], v[120:123]
	v_mfma_f32_16x16x32_bf16 v[108:111], v[132:135], v[194:197], v[108:111]
	v_mfma_f32_16x16x32_bf16 v[104:107], v[158:161], v[194:197], v[104:107]
	v_mfma_f32_16x16x32_bf16 v[92:95], v[132:135], v[206:209], v[92:95]
	v_mfma_f32_16x16x32_bf16 v[88:91], v[158:161], v[206:209], v[88:91]
	s_waitcnt lgkmcnt(0)
	v_mfma_f32_16x16x32_bf16 v[76:79], v[132:135], v[214:217], v[76:79]
	v_mfma_f32_16x16x32_bf16 v[72:75], v[158:161], v[214:217], v[72:75]
	v_mfma_f32_16x16x32_bf16 v[116:119], v[162:165], v[182:185], v[116:119]
	v_mfma_f32_16x16x32_bf16 v[112:115], v[174:177], v[182:185], v[112:115]
	v_mfma_f32_16x16x32_bf16 v[100:103], v[162:165], v[190:193], v[100:103]
	v_mfma_f32_16x16x32_bf16 v[96:99], v[174:177], v[190:193], v[96:99]
	v_mfma_f32_16x16x32_bf16 v[84:87], v[162:165], v[198:201], v[84:87]
	v_mfma_f32_16x16x32_bf16 v[80:83], v[174:177], v[198:201], v[80:83]
	v_mfma_f32_16x16x32_bf16 v[68:71], v[162:165], v[210:213], v[68:71]
	v_mfma_f32_16x16x32_bf16 v[64:67], v[174:177], v[210:213], v[64:67]
	v_mfma_f32_16x16x32_bf16 v[116:119], v[166:169], v[186:189], v[116:119]
	v_mfma_f32_16x16x32_bf16 v[112:115], v[178:181], v[186:189], v[112:115]
	v_mfma_f32_16x16x32_bf16 v[100:103], v[166:169], v[194:197], v[100:103]
	v_mfma_f32_16x16x32_bf16 v[96:99], v[178:181], v[194:197], v[96:99]
	v_mfma_f32_16x16x32_bf16 v[84:87], v[166:169], v[206:209], v[84:87]
	v_mfma_f32_16x16x32_bf16 v[80:83], v[178:181], v[206:209], v[80:83]
	v_mfma_f32_16x16x32_bf16 v[68:71], v[166:169], v[214:217], v[68:71]
	v_mfma_f32_16x16x32_bf16 v[64:67], v[178:181], v[214:217], v[64:67]
	s_setprio 0
	s_barrier
; #define PG8_STAGE(bufoff, gbase, voff) do { _Pragma("unroll") for (int _i = 0; _i < 2; ++_i) \
;         __builtin_amdgcn_global_load_lds((const unsigned*)((const char*)(gbase) + (voff)[_i]), (LAS unsigned*)(lds + (bufoff) + ldsw + _i * 8192), 16, 0, 0); } while (0)
; #define PG8_LDA(dst, b, h) do { _Pragma("unroll") for (int m = 0; m < 4; ++m) _Pragma("unroll") for (int k = 0; k < 2; ++k) dst[m][k] = *(const LAS bf16x8*)(lds + PG8_SA(b, h) + aoff + m * 2048 + k * 1024); } while (0)
; #define PG8_MMA(ai, bj, At, Bt) do { __builtin_amdgcn_s_setprio(1); _Pragma("unroll") for (int m = 0; m < 4; ++m) _Pragma("unroll") for (int n = 0; n < 2; ++n) _Pragma("unroll") for (int k = 0; k < 2; ++k) \
;         acc[ai][bj][m][n] = __builtin_amdgcn_mfma_f32_16x16x32_bf16(Bt[n][k], At[m][k], acc[ai][bj][m][n], 0, 0, 0); __builtin_amdgcn_s_setprio(0); } while (0)
; #define PG8_WAIT_V(n) asm volatile("s_waitcnt vmcnt(" #n ")" ::: "memory")
; #define PG8_WAIT_L(n) asm volatile("s_waitcnt lgkmcnt(" #n ")" ::: "memory")
; #define PG8_BAR __builtin_amdgcn_s_barrier()
; #define PG8_SCHED __builtin_amdgcn_sched_barrier(0)
; __device__ __forceinline__ void gemm_phase(LAS unsigned char* lds, const Desc& g, int G, int cidx, int tid) {
;     ...
;             PG8_LDA(At, 1, 1); PG8_STAGE(PG8_SB(1, 0), b3, voffB); PG8_STAGE(PG8_SB(1, 1), b3 + hstepB, voffB); PG8_STAGE(PG8_SA(1, 0), a3, voffA);
;             PG8_WAIT_V(8); PG8_WAIT_L(0); PG8_BAR; PG8_MMA(1, 0, At, B0); PG8_MMA(1, 1, At, B1); PG8_BAR; PG8_SCHED;
;         }
;         if (wr == 0) PG8_BAR;
	s_add_i32 s4, s4, s88
	v_lshl_add_u64 v[218:219], v[218:219], 0, s[22:23]
	s_mov_b32 m0, s4
	ds_read_b128 v[182:185], v172 offset:49152
	ds_read_b128 v[186:189], v172 offset:50176
	ds_read_b128 v[190:193], v172 offset:51200
	ds_read_b128 v[194:197], v172 offset:52224
	ds_read_b128 v[198:201], v172 offset:53248
	ds_read_b128 v[206:209], v172 offset:54272
	ds_read_b128 v[210:213], v172 offset:55296
	ds_read_b128 v[214:217], v172 offset:56320
	global_load_lds_dwordx4 v[218:219], off
	v_lshl_add_u64 v[218:219], v[220:221], 0, s[22:23]
	s_add_i32 m0, s4, 0x2000
	s_add_i32 s4, s5, s88
	global_load_lds_dwordx4 v[218:219], off
	v_lshl_add_u64 v[218:219], v[222:223], 0, s[22:23]
	s_mov_b32 m0, s4
	s_nop 0
	global_load_lds_dwordx4 v[218:219], off
	v_lshl_add_u64 v[218:219], v[224:225], 0, s[22:23]
	s_add_i32 m0, s4, 0x2000
	s_nop 0
	global_load_lds_dwordx4 v[218:219], off
	v_lshl_add_u64 v[218:219], v[226:227], 0, s[22:23]
	s_mov_b32 m0, s54
	s_nop 0
	global_load_lds_dwordx4 v[218:219], off
	v_lshl_add_u64 v[218:219], v[228:229], 0, s[22:23]
	s_mov_b32 m0, s55
	s_nop 0
	global_load_lds_dwordx4 v[218:219], off
	s_waitcnt vmcnt(8)
	s_barrier
	s_setprio 1
	s_waitcnt lgkmcnt(7)
	v_mfma_f32_16x16x32_bf16 v[60:63], v[128:131], v[182:185], v[60:63]
	v_mfma_f32_16x16x32_bf16 v[56:59], v[146:149], v[182:185], v[56:59]
	s_waitcnt lgkmcnt(5)
	v_mfma_f32_16x16x32_bf16 v[44:47], v[128:131], v[190:193], v[44:47]
	v_mfma_f32_16x16x32_bf16 v[40:43], v[146:149], v[190:193], v[40:43]
	s_waitcnt lgkmcnt(3)
	v_mfma_f32_16x16x32_bf16 v[28:31], v[128:131], v[198:201], v[28:31]
	v_mfma_f32_16x16x32_bf16 v[24:27], v[146:149], v[198:201], v[24:27]
	s_waitcnt lgkmcnt(1)
	v_mfma_f32_16x16x32_bf16 v[12:15], v[128:131], v[210:213], v[12:15]
	v_mfma_f32_16x16x32_bf16 v[8:11], v[146:149], v[210:213], v[8:11]
	v_mfma_f32_16x16x32_bf16 v[60:63], v[132:135], v[186:189], v[60:63]
	v_mfma_f32_16x16x32_bf16 v[56:59], v[158:161], v[186:189], v[56:59]
	v_mfma_f32_16x16x32_bf16 v[44:47], v[132:135], v[194:197], v[44:47]
	v_mfma_f32_16x16x32_bf16 v[40:43], v[158:161], v[194:197], v[40:43]
	v_mfma_f32_16x16x32_bf16 v[28:31], v[132:135], v[206:209], v[28:31]
	v_mfma_f32_16x16x32_bf16 v[24:27], v[158:161], v[206:209], v[24:27]
	s_waitcnt lgkmcnt(0)
	v_mfma_f32_16x16x32_bf16 v[12:15], v[132:135], v[214:217], v[12:15]
	v_mfma_f32_16x16x32_bf16 v[8:11], v[158:161], v[214:217], v[8:11]
	v_mfma_f32_16x16x32_bf16 v[52:55], v[162:165], v[182:185], v[52:55]
	v_mfma_f32_16x16x32_bf16 v[48:51], v[174:177], v[182:185], v[48:51]
	v_mfma_f32_16x16x32_bf16 v[36:39], v[162:165], v[190:193], v[36:39]
	v_mfma_f32_16x16x32_bf16 v[32:35], v[174:177], v[190:193], v[32:35]
	v_mfma_f32_16x16x32_bf16 v[20:23], v[162:165], v[198:201], v[20:23]
	v_mfma_f32_16x16x32_bf16 v[16:19], v[174:177], v[198:201], v[16:19]
	v_mfma_f32_16x16x32_bf16 v[0:3], v[162:165], v[210:213], v[0:3]
	v_mfma_f32_16x16x32_bf16 v[4:7], v[174:177], v[210:213], v[4:7]
	v_mfma_f32_16x16x32_bf16 v[52:55], v[166:169], v[186:189], v[52:55]
	v_mfma_f32_16x16x32_bf16 v[48:51], v[178:181], v[186:189], v[48:51]
	v_mfma_f32_16x16x32_bf16 v[36:39], v[166:169], v[194:197], v[36:39]
	v_mfma_f32_16x16x32_bf16 v[32:35], v[178:181], v[194:197], v[32:35]
	v_mfma_f32_16x16x32_bf16 v[20:23], v[166:169], v[206:209], v[20:23]
	v_mfma_f32_16x16x32_bf16 v[16:19], v[178:181], v[206:209], v[16:19]
	v_mfma_f32_16x16x32_bf16 v[0:3], v[166:169], v[214:217], v[0:3]
	v_mfma_f32_16x16x32_bf16 v[4:7], v[178:181], v[214:217], v[4:7]
	s_setprio 0
	s_barrier
	s_add_u32 s67, s67, 0x100
	s_addc_u32 s75, s75, 0
	s_add_u32 s0, s0, 0x100
	s_addc_u32 s1, s1, 0
	s_cmp_ge_u32 s72, s6
	s_mov_b32 s40, s72
	s_cbranch_scc0 .LBB0_310
	s_and_b64 vcc, exec, s[8:9]
	s_cbranch_vccz .LBB0_313
	s_barrier
